# GEMM K-loops: no priority drop between the two 16-MFMA groups of a block
# baseline (speedup 1.0000x reference)
.LBB0_144:
	v_add_u32_e32 v158, s84, v222
	ds_read_b128 v[130:133], v225
	ds_read_b128 v[134:137], v225 offset:1024
	ds_read_b128 v[138:141], v225 offset:2048
	ds_read_b128 v[142:145], v225 offset:3072
	ds_read_b128 v[146:149], v158
	ds_read_b128 v[150:153], v158 offset:1024
	ds_read_b128 v[154:157], v158 offset:2048
	ds_read_b128 v[158:161], v158 offset:3072
	s_add_u32 s12, s8, 0xfffc0080
	s_addc_u32 s13, s9, -1
	s_cmp_eq_u32 s62, 12
	s_cselect_b32 s15, s11, s13
	s_cselect_b32 s14, s26, s12
	s_cselect_b32 s13, s47, s61
	s_cselect_b32 s12, s49, s60
	v_lshl_add_u64 v[216:217], s[8:9], 0, v[200:201]
	s_add_i32 m0, s25, 0xc000
	ds_read_b128 v[162:165], v223
	ds_read_b128 v[208:211], v223 offset:1024
	ds_read_b128 v[212:215], v223 offset:2048
	ds_read_b128 v[226:229], v223 offset:3072
	ds_read_b128 v[230:233], v223 offset:4096
	ds_read_b128 v[234:237], v223 offset:5120
	ds_read_b128 v[238:241], v223 offset:6144
	ds_read_b128 v[242:245], v223 offset:7168
	global_load_lds_dwordx4 v[216:217], off
	v_lshl_add_u64 v[216:217], s[8:9], 0, v[202:203]
	s_add_i32 m0, s25, 0xe000
	s_nop 0
	global_load_lds_dwordx4 v[216:217], off
	s_waitcnt vmcnt(8)
	s_waitcnt lgkmcnt(0)
	s_barrier
	s_setprio 1
	s_waitcnt lgkmcnt(0)
	v_mfma_f32_16x16x32_bf16 v[126:129], v[130:133], v[162:165], v[126:129]
	v_mfma_f32_16x16x32_bf16 v[122:125], v[138:141], v[162:165], v[122:125]
	v_mfma_f32_16x16x32_bf16 v[110:113], v[130:133], v[212:215], v[110:113]
	v_mfma_f32_16x16x32_bf16 v[106:109], v[138:141], v[212:215], v[106:109]
	v_mfma_f32_16x16x32_bf16 v[94:97], v[130:133], v[230:233], v[94:97]
	v_mfma_f32_16x16x32_bf16 v[90:93], v[138:141], v[230:233], v[90:93]
	v_mfma_f32_16x16x32_bf16 v[78:81], v[130:133], v[238:241], v[78:81]
	v_mfma_f32_16x16x32_bf16 v[74:77], v[138:141], v[238:241], v[74:77]
	v_mfma_f32_16x16x32_bf16 v[126:129], v[134:137], v[208:211], v[126:129]
	v_mfma_f32_16x16x32_bf16 v[122:125], v[142:145], v[208:211], v[122:125]
	v_mfma_f32_16x16x32_bf16 v[110:113], v[134:137], v[226:229], v[110:113]
	v_mfma_f32_16x16x32_bf16 v[106:109], v[142:145], v[226:229], v[106:109]
	v_mfma_f32_16x16x32_bf16 v[94:97], v[134:137], v[234:237], v[94:97]
	v_mfma_f32_16x16x32_bf16 v[90:93], v[142:145], v[234:237], v[90:93]
	v_mfma_f32_16x16x32_bf16 v[78:81], v[134:137], v[242:245], v[78:81]
	v_mfma_f32_16x16x32_bf16 v[74:77], v[142:145], v[242:245], v[74:77]
	v_mfma_f32_16x16x32_bf16 v[118:121], v[146:149], v[162:165], v[118:121]
	v_mfma_f32_16x16x32_bf16 v[114:117], v[154:157], v[162:165], v[114:117]
	v_mfma_f32_16x16x32_bf16 v[102:105], v[146:149], v[212:215], v[102:105]
	v_mfma_f32_16x16x32_bf16 v[98:101], v[154:157], v[212:215], v[98:101]
	v_mfma_f32_16x16x32_bf16 v[86:89], v[146:149], v[230:233], v[86:89]
	v_mfma_f32_16x16x32_bf16 v[82:85], v[154:157], v[230:233], v[82:85]
	v_mfma_f32_16x16x32_bf16 v[70:73], v[146:149], v[238:241], v[70:73]
	v_mfma_f32_16x16x32_bf16 v[66:69], v[154:157], v[238:241], v[66:69]
	v_mfma_f32_16x16x32_bf16 v[118:121], v[150:153], v[208:211], v[118:121]
	v_mfma_f32_16x16x32_bf16 v[114:117], v[158:161], v[208:211], v[114:117]
	v_mfma_f32_16x16x32_bf16 v[102:105], v[150:153], v[226:229], v[102:105]
	v_mfma_f32_16x16x32_bf16 v[98:101], v[158:161], v[226:229], v[98:101]
	v_mfma_f32_16x16x32_bf16 v[86:89], v[150:153], v[234:237], v[86:89]
	v_mfma_f32_16x16x32_bf16 v[82:85], v[158:161], v[234:237], v[82:85]
	v_mfma_f32_16x16x32_bf16 v[70:73], v[150:153], v[242:245], v[70:73]
	v_mfma_f32_16x16x32_bf16 v[66:69], v[158:161], v[242:245], v[66:69]
	s_setprio 0
	s_barrier
	s_add_i32 s54, s83, s72
	v_lshl_add_u64 v[216:217], s[12:13], 0, v[168:169]
	s_mov_b32 m0, s54
	ds_read_b128 v[162:165], v223 offset:16384
	ds_read_b128 v[208:211], v223 offset:17408
	ds_read_b128 v[212:215], v223 offset:18432
	ds_read_b128 v[226:229], v223 offset:19456
	ds_read_b128 v[230:233], v223 offset:20480
	ds_read_b128 v[234:237], v223 offset:21504
	ds_read_b128 v[238:241], v223 offset:22528
	ds_read_b128 v[242:245], v223 offset:23552
	global_load_lds_dwordx4 v[216:217], off
	s_add_i32 m0, s54, 0x2000
	s_add_u32 s56, s12, 0x40000
	v_lshl_add_u64 v[246:247], s[12:13], 0, v[172:173]
	s_addc_u32 s57, s13, 0
	s_add_i32 s54, s84, s72
	global_load_lds_dwordx4 v[246:247], off
	v_lshl_add_u64 v[248:249], s[56:57], 0, v[168:169]
	s_mov_b32 m0, s54
	v_lshl_add_u64 v[250:251], s[14:15], 0, v[170:171]
	global_load_lds_dwordx4 v[248:249], off
	v_lshl_add_u64 v[248:249], s[56:57], 0, v[172:173]
	s_add_i32 m0, s54, 0x2000
	s_nop 0
	global_load_lds_dwordx4 v[248:249], off
	v_lshl_add_u64 v[248:249], s[14:15], 0, v[166:167]
	s_mov_b32 m0, s25
	s_nop 0
	global_load_lds_dwordx4 v[248:249], off
	s_mov_b32 m0, s73
	s_nop 0
	global_load_lds_dwordx4 v[250:251], off
	s_waitcnt vmcnt(8)
	s_waitcnt lgkmcnt(0)
	s_barrier
	s_setprio 1
	s_waitcnt lgkmcnt(0)
	v_mfma_f32_16x16x32_bf16 v[62:65], v[130:133], v[162:165], v[62:65]
	v_mfma_f32_16x16x32_bf16 v[58:61], v[138:141], v[162:165], v[58:61]
	v_mfma_f32_16x16x32_bf16 v[46:49], v[130:133], v[212:215], v[46:49]
	v_mfma_f32_16x16x32_bf16 v[42:45], v[138:141], v[212:215], v[42:45]
	v_mfma_f32_16x16x32_bf16 v[30:33], v[130:133], v[230:233], v[30:33]
	v_mfma_f32_16x16x32_bf16 v[26:29], v[138:141], v[230:233], v[26:29]
	v_mfma_f32_16x16x32_bf16 v[14:17], v[130:133], v[238:241], v[14:17]
	v_mfma_f32_16x16x32_bf16 v[10:13], v[138:141], v[238:241], v[10:13]
	v_mfma_f32_16x16x32_bf16 v[62:65], v[134:137], v[208:211], v[62:65]
	v_mfma_f32_16x16x32_bf16 v[58:61], v[142:145], v[208:211], v[58:61]
	v_mfma_f32_16x16x32_bf16 v[46:49], v[134:137], v[226:229], v[46:49]
	v_mfma_f32_16x16x32_bf16 v[42:45], v[142:145], v[226:229], v[42:45]
	v_mfma_f32_16x16x32_bf16 v[30:33], v[134:137], v[234:237], v[30:33]
	v_mfma_f32_16x16x32_bf16 v[26:29], v[142:145], v[234:237], v[26:29]
	v_mfma_f32_16x16x32_bf16 v[14:17], v[134:137], v[242:245], v[14:17]
	v_mfma_f32_16x16x32_bf16 v[10:13], v[142:145], v[242:245], v[10:13]
	v_mfma_f32_16x16x32_bf16 v[54:57], v[146:149], v[162:165], v[54:57]
	v_mfma_f32_16x16x32_bf16 v[50:53], v[154:157], v[162:165], v[50:53]
	v_mfma_f32_16x16x32_bf16 v[38:41], v[146:149], v[212:215], v[38:41]
	v_mfma_f32_16x16x32_bf16 v[34:37], v[154:157], v[212:215], v[34:37]
	v_mfma_f32_16x16x32_bf16 v[22:25], v[146:149], v[230:233], v[22:25]
	v_mfma_f32_16x16x32_bf16 v[18:21], v[154:157], v[230:233], v[18:21]
	v_mfma_f32_16x16x32_bf16 v[6:9], v[146:149], v[238:241], v[6:9]
	v_mfma_f32_16x16x32_bf16 v[2:5], v[154:157], v[238:241], v[2:5]
	v_mfma_f32_16x16x32_bf16 v[54:57], v[150:153], v[208:211], v[54:57]
	v_mfma_f32_16x16x32_bf16 v[50:53], v[158:161], v[208:211], v[50:53]
	v_mfma_f32_16x16x32_bf16 v[38:41], v[150:153], v[226:229], v[38:41]
	v_mfma_f32_16x16x32_bf16 v[34:37], v[158:161], v[226:229], v[34:37]
	v_mfma_f32_16x16x32_bf16 v[22:25], v[150:153], v[234:237], v[22:25]
	v_mfma_f32_16x16x32_bf16 v[18:21], v[158:161], v[234:237], v[18:21]
	v_mfma_f32_16x16x32_bf16 v[6:9], v[150:153], v[242:245], v[6:9]
	v_mfma_f32_16x16x32_bf16 v[2:5], v[158:161], v[242:245], v[2:5]
	s_setprio 0
	s_barrier
	s_add_i32 s54, 0, 0x18000
	s_add_i32 s55, 0, 0x1c000
	v_add_u32_e32 v142, s54, v222
	v_add_u32_e32 v158, s55, v222
	ds_read_b128 v[130:133], v142
	ds_read_b128 v[134:137], v142 offset:1024
	ds_read_b128 v[138:141], v142 offset:2048
	ds_read_b128 v[142:145], v142 offset:3072
	ds_read_b128 v[146:149], v158
	ds_read_b128 v[150:153], v158 offset:1024
	ds_read_b128 v[154:157], v158 offset:2048
	ds_read_b128 v[158:161], v158 offset:3072
	s_add_u32 s14, s14, 0x40000
	s_addc_u32 s15, s15, 0
	s_mov_b32 m0, s74
	v_lshl_add_u64 v[252:253], s[14:15], 0, v[166:167]
	ds_read_b128 v[162:165], v223 offset:32768
	ds_read_b128 v[208:211], v223 offset:33792
	ds_read_b128 v[212:215], v223 offset:34816
	ds_read_b128 v[226:229], v223 offset:35840
	ds_read_b128 v[230:233], v223 offset:36864
	ds_read_b128 v[234:237], v223 offset:37888
	ds_read_b128 v[238:241], v223 offset:38912
	ds_read_b128 v[242:245], v223 offset:39936
	global_load_lds_dwordx4 v[252:253], off
	v_lshl_add_u64 v[252:253], s[14:15], 0, v[170:171]
	s_mov_b32 m0, s75
	s_nop 0
	global_load_lds_dwordx4 v[252:253], off
	s_waitcnt vmcnt(8)
	s_waitcnt lgkmcnt(0)
	s_barrier
	s_setprio 1
	s_waitcnt lgkmcnt(0)
	v_mfma_f32_16x16x32_bf16 v[126:129], v[130:133], v[162:165], v[126:129]
	v_mfma_f32_16x16x32_bf16 v[122:125], v[138:141], v[162:165], v[122:125]
	v_mfma_f32_16x16x32_bf16 v[110:113], v[130:133], v[212:215], v[110:113]
	v_mfma_f32_16x16x32_bf16 v[106:109], v[138:141], v[212:215], v[106:109]
	v_mfma_f32_16x16x32_bf16 v[94:97], v[130:133], v[230:233], v[94:97]
	v_mfma_f32_16x16x32_bf16 v[90:93], v[138:141], v[230:233], v[90:93]
	v_mfma_f32_16x16x32_bf16 v[78:81], v[130:133], v[238:241], v[78:81]
	v_mfma_f32_16x16x32_bf16 v[74:77], v[138:141], v[238:241], v[74:77]
	v_mfma_f32_16x16x32_bf16 v[126:129], v[134:137], v[208:211], v[126:129]
	v_mfma_f32_16x16x32_bf16 v[122:125], v[142:145], v[208:211], v[122:125]
	v_mfma_f32_16x16x32_bf16 v[110:113], v[134:137], v[226:229], v[110:113]
	v_mfma_f32_16x16x32_bf16 v[106:109], v[142:145], v[226:229], v[106:109]
	v_mfma_f32_16x16x32_bf16 v[94:97], v[134:137], v[234:237], v[94:97]
	v_mfma_f32_16x16x32_bf16 v[90:93], v[142:145], v[234:237], v[90:93]
	v_mfma_f32_16x16x32_bf16 v[78:81], v[134:137], v[242:245], v[78:81]
	v_mfma_f32_16x16x32_bf16 v[74:77], v[142:145], v[242:245], v[74:77]
	v_mfma_f32_16x16x32_bf16 v[118:121], v[146:149], v[162:165], v[118:121]
	v_mfma_f32_16x16x32_bf16 v[114:117], v[154:157], v[162:165], v[114:117]
	v_mfma_f32_16x16x32_bf16 v[102:105], v[146:149], v[212:215], v[102:105]
	v_mfma_f32_16x16x32_bf16 v[98:101], v[154:157], v[212:215], v[98:101]
	v_mfma_f32_16x16x32_bf16 v[86:89], v[146:149], v[230:233], v[86:89]
	v_mfma_f32_16x16x32_bf16 v[82:85], v[154:157], v[230:233], v[82:85]
	v_mfma_f32_16x16x32_bf16 v[70:73], v[146:149], v[238:241], v[70:73]
	v_mfma_f32_16x16x32_bf16 v[66:69], v[154:157], v[238:241], v[66:69]
	v_mfma_f32_16x16x32_bf16 v[118:121], v[150:153], v[208:211], v[118:121]
	v_mfma_f32_16x16x32_bf16 v[114:117], v[158:161], v[208:211], v[114:117]
	v_mfma_f32_16x16x32_bf16 v[102:105], v[150:153], v[226:229], v[102:105]
	v_mfma_f32_16x16x32_bf16 v[98:101], v[158:161], v[226:229], v[98:101]
	v_mfma_f32_16x16x32_bf16 v[86:89], v[150:153], v[234:237], v[86:89]
	v_mfma_f32_16x16x32_bf16 v[82:85], v[158:161], v[234:237], v[82:85]
	v_mfma_f32_16x16x32_bf16 v[70:73], v[150:153], v[242:245], v[70:73]
	v_mfma_f32_16x16x32_bf16 v[66:69], v[158:161], v[242:245], v[66:69]
	s_setprio 0
	s_barrier
	s_add_i32 s14, s54, s72
	v_lshl_add_u64 v[216:217], v[216:217], 0, s[38:39]
	s_mov_b32 m0, s14
	ds_read_b128 v[162:165], v223 offset:49152
	ds_read_b128 v[208:211], v223 offset:50176
	ds_read_b128 v[212:215], v223 offset:51200
	ds_read_b128 v[226:229], v223 offset:52224
	ds_read_b128 v[230:233], v223 offset:53248
	ds_read_b128 v[234:237], v223 offset:54272
	ds_read_b128 v[238:241], v223 offset:55296
	ds_read_b128 v[242:245], v223 offset:56320
	global_load_lds_dwordx4 v[216:217], off
	s_add_i32 m0, s14, 0x2000
	s_add_u32 s12, s12, 0x40080
	v_lshl_add_u64 v[216:217], v[246:247], 0, s[38:39]
	s_addc_u32 s13, s13, 0
	s_add_i32 s14, s55, s72
	global_load_lds_dwordx4 v[216:217], off
	v_lshl_add_u64 v[216:217], s[12:13], 0, v[168:169]
	s_mov_b32 m0, s14
	s_nop 0
	global_load_lds_dwordx4 v[216:217], off
	v_lshl_add_u64 v[216:217], s[12:13], 0, v[172:173]
	s_add_i32 m0, s14, 0x2000
	s_nop 0
	global_load_lds_dwordx4 v[216:217], off
	v_lshl_add_u64 v[216:217], v[248:249], 0, s[38:39]
	s_mov_b32 m0, s78
	s_nop 0
	global_load_lds_dwordx4 v[216:217], off
	v_lshl_add_u64 v[216:217], v[250:251], 0, s[38:39]
	s_mov_b32 m0, s79
	s_nop 0
	global_load_lds_dwordx4 v[216:217], off
	s_waitcnt vmcnt(8)
	s_waitcnt lgkmcnt(0)
	s_barrier
	s_setprio 1
	s_waitcnt lgkmcnt(0)
	v_mfma_f32_16x16x32_bf16 v[62:65], v[130:133], v[162:165], v[62:65]
	v_mfma_f32_16x16x32_bf16 v[58:61], v[138:141], v[162:165], v[58:61]
	v_mfma_f32_16x16x32_bf16 v[46:49], v[130:133], v[212:215], v[46:49]
	v_mfma_f32_16x16x32_bf16 v[42:45], v[138:141], v[212:215], v[42:45]
	v_mfma_f32_16x16x32_bf16 v[30:33], v[130:133], v[230:233], v[30:33]
	v_mfma_f32_16x16x32_bf16 v[26:29], v[138:141], v[230:233], v[26:29]
	v_mfma_f32_16x16x32_bf16 v[14:17], v[130:133], v[238:241], v[14:17]
	v_mfma_f32_16x16x32_bf16 v[10:13], v[138:141], v[238:241], v[10:13]
	v_mfma_f32_16x16x32_bf16 v[62:65], v[134:137], v[208:211], v[62:65]
	v_mfma_f32_16x16x32_bf16 v[58:61], v[142:145], v[208:211], v[58:61]
	v_mfma_f32_16x16x32_bf16 v[46:49], v[134:137], v[226:229], v[46:49]
	v_mfma_f32_16x16x32_bf16 v[42:45], v[142:145], v[226:229], v[42:45]
	v_mfma_f32_16x16x32_bf16 v[30:33], v[134:137], v[234:237], v[30:33]
	v_mfma_f32_16x16x32_bf16 v[26:29], v[142:145], v[234:237], v[26:29]
	v_mfma_f32_16x16x32_bf16 v[14:17], v[134:137], v[242:245], v[14:17]
	v_mfma_f32_16x16x32_bf16 v[10:13], v[142:145], v[242:245], v[10:13]
	v_mfma_f32_16x16x32_bf16 v[54:57], v[146:149], v[162:165], v[54:57]
	v_mfma_f32_16x16x32_bf16 v[50:53], v[154:157], v[162:165], v[50:53]
	v_mfma_f32_16x16x32_bf16 v[38:41], v[146:149], v[212:215], v[38:41]
	v_mfma_f32_16x16x32_bf16 v[34:37], v[154:157], v[212:215], v[34:37]
	v_mfma_f32_16x16x32_bf16 v[22:25], v[146:149], v[230:233], v[22:25]
	v_mfma_f32_16x16x32_bf16 v[18:21], v[154:157], v[230:233], v[18:21]
	v_mfma_f32_16x16x32_bf16 v[6:9], v[146:149], v[238:241], v[6:9]
	v_mfma_f32_16x16x32_bf16 v[2:5], v[154:157], v[238:241], v[2:5]
	v_mfma_f32_16x16x32_bf16 v[54:57], v[150:153], v[208:211], v[54:57]
	v_mfma_f32_16x16x32_bf16 v[50:53], v[158:161], v[208:211], v[50:53]
	v_mfma_f32_16x16x32_bf16 v[38:41], v[150:153], v[226:229], v[38:41]
	v_mfma_f32_16x16x32_bf16 v[34:37], v[158:161], v[226:229], v[34:37]
	v_mfma_f32_16x16x32_bf16 v[22:25], v[150:153], v[234:237], v[22:25]
	v_mfma_f32_16x16x32_bf16 v[18:21], v[158:161], v[234:237], v[18:21]
	v_mfma_f32_16x16x32_bf16 v[6:9], v[150:153], v[242:245], v[6:9]
	v_mfma_f32_16x16x32_bf16 v[2:5], v[158:161], v[242:245], v[2:5]
	s_setprio 0
	s_barrier
	s_add_i32 s62, s62, 2
	s_add_u32 s8, s8, 0x100
	s_addc_u32 s9, s9, 0
	s_add_u32 s60, s60, 0x100
	s_addc_u32 s61, s61, 0
	s_cmp_gt_u32 s62, 13
	s_cbranch_scc0 .LBB0_144
	s_and_b64 vcc, exec, s[40:41]
	s_cbranch_vccz .LBB0_147
	s_barrier

.LBB0_647:
	ds_read_b128 v[154:157], v150
	ds_read_b128 v[158:161], v150 offset:1024
	ds_read_b128 v[162:165], v150 offset:2048
	ds_read_b128 v[166:169], v150 offset:3072
	ds_read_b128 v[170:173], v151
	ds_read_b128 v[174:177], v151 offset:1024
	ds_read_b128 v[178:181], v151 offset:2048
	ds_read_b128 v[186:189], v151 offset:3072
	s_add_u32 s40, s38, 0xfffc0080
	s_addc_u32 s41, s39, -1
	s_cmp_eq_u32 s74, 12
	s_cselect_b32 s43, s27, s41
	s_cselect_b32 s42, s68, s40
	s_cselect_b32 s41, s25, s73
	s_cselect_b32 s40, s69, s72
	v_lshl_add_u64 v[146:147], s[38:39], 0, v[138:139]
	s_add_i32 m0, s37, 0xc000
	ds_read_b128 v[190:193], v152
	ds_read_b128 v[194:197], v152 offset:1024
	ds_read_b128 v[198:201], v152 offset:2048
	ds_read_b128 v[202:205], v152 offset:3072
	ds_read_b128 v[206:209], v152 offset:4096
	ds_read_b128 v[210:213], v152 offset:5120
	ds_read_b128 v[214:217], v152 offset:6144
	ds_read_b128 v[218:221], v152 offset:7168
	global_load_lds_dwordx4 v[146:147], off
	v_lshl_add_u64 v[146:147], s[38:39], 0, v[140:141]
	s_add_i32 m0, s37, 0xe000
	s_nop 0
	global_load_lds_dwordx4 v[146:147], off
	s_waitcnt vmcnt(8)
	s_waitcnt lgkmcnt(0)
	s_barrier
	s_setprio 1
	s_waitcnt lgkmcnt(0)
	v_mfma_f32_16x16x32_bf16 v[126:129], v[154:157], v[190:193], v[126:129]
	v_mfma_f32_16x16x32_bf16 v[122:125], v[162:165], v[190:193], v[122:125]
	v_mfma_f32_16x16x32_bf16 v[118:121], v[154:157], v[198:201], v[118:121]
	v_mfma_f32_16x16x32_bf16 v[110:113], v[162:165], v[198:201], v[110:113]
	v_mfma_f32_16x16x32_bf16 v[102:105], v[154:157], v[206:209], v[102:105]
	v_mfma_f32_16x16x32_bf16 v[94:97], v[162:165], v[206:209], v[94:97]
	v_mfma_f32_16x16x32_bf16 v[86:89], v[154:157], v[214:217], v[86:89]
	v_mfma_f32_16x16x32_bf16 v[78:81], v[162:165], v[214:217], v[78:81]
	v_mfma_f32_16x16x32_bf16 v[126:129], v[158:161], v[194:197], v[126:129]
	v_mfma_f32_16x16x32_bf16 v[122:125], v[166:169], v[194:197], v[122:125]
	v_mfma_f32_16x16x32_bf16 v[118:121], v[158:161], v[202:205], v[118:121]
	v_mfma_f32_16x16x32_bf16 v[110:113], v[166:169], v[202:205], v[110:113]
	v_mfma_f32_16x16x32_bf16 v[102:105], v[158:161], v[210:213], v[102:105]
	v_mfma_f32_16x16x32_bf16 v[94:97], v[166:169], v[210:213], v[94:97]
	v_mfma_f32_16x16x32_bf16 v[86:89], v[158:161], v[218:221], v[86:89]
	v_mfma_f32_16x16x32_bf16 v[78:81], v[166:169], v[218:221], v[78:81]
	v_mfma_f32_16x16x32_bf16 v[114:117], v[170:173], v[190:193], v[114:117]
	v_mfma_f32_16x16x32_bf16 v[106:109], v[178:181], v[190:193], v[106:109]
	v_mfma_f32_16x16x32_bf16 v[98:101], v[170:173], v[198:201], v[98:101]
	v_mfma_f32_16x16x32_bf16 v[90:93], v[178:181], v[198:201], v[90:93]
	v_mfma_f32_16x16x32_bf16 v[82:85], v[170:173], v[206:209], v[82:85]
	v_mfma_f32_16x16x32_bf16 v[74:77], v[178:181], v[206:209], v[74:77]
	v_mfma_f32_16x16x32_bf16 v[70:73], v[170:173], v[214:217], v[70:73]
	v_mfma_f32_16x16x32_bf16 v[66:69], v[178:181], v[214:217], v[66:69]
	v_mfma_f32_16x16x32_bf16 v[114:117], v[174:177], v[194:197], v[114:117]
	v_mfma_f32_16x16x32_bf16 v[106:109], v[186:189], v[194:197], v[106:109]
	v_mfma_f32_16x16x32_bf16 v[98:101], v[174:177], v[202:205], v[98:101]
	v_mfma_f32_16x16x32_bf16 v[90:93], v[186:189], v[202:205], v[90:93]
	v_mfma_f32_16x16x32_bf16 v[82:85], v[174:177], v[210:213], v[82:85]
	v_mfma_f32_16x16x32_bf16 v[74:77], v[186:189], v[210:213], v[74:77]
	v_mfma_f32_16x16x32_bf16 v[70:73], v[174:177], v[218:221], v[70:73]
	v_mfma_f32_16x16x32_bf16 v[66:69], v[186:189], v[218:221], v[66:69]
	s_setprio 0
	s_barrier
	s_add_i32 s54, s60, s45
	v_lshl_add_u64 v[146:147], s[40:41], 0, v[132:133]
	s_mov_b32 m0, s54
	ds_read_b128 v[190:193], v152 offset:16384
	ds_read_b128 v[194:197], v152 offset:17408
	ds_read_b128 v[198:201], v152 offset:18432
	ds_read_b128 v[202:205], v152 offset:19456
	ds_read_b128 v[206:209], v152 offset:20480
	ds_read_b128 v[210:213], v152 offset:21504
	ds_read_b128 v[214:217], v152 offset:22528
	ds_read_b128 v[218:221], v152 offset:23552
	global_load_lds_dwordx4 v[146:147], off
	s_add_i32 m0, s54, 0x2000
	s_add_u32 s54, s40, 0x40000
	v_lshl_add_u64 v[182:183], s[40:41], 0, v[136:137]
	s_addc_u32 s55, s41, 0
	s_add_i32 s56, s61, s45
	global_load_lds_dwordx4 v[182:183], off
	v_lshl_add_u64 v[222:223], s[54:55], 0, v[132:133]
	s_mov_b32 m0, s56
	v_lshl_add_u64 v[224:225], s[42:43], 0, v[134:135]
	global_load_lds_dwordx4 v[222:223], off
	v_lshl_add_u64 v[222:223], s[54:55], 0, v[136:137]
	s_add_i32 m0, s56, 0x2000
	s_nop 0
	global_load_lds_dwordx4 v[222:223], off
	v_lshl_add_u64 v[222:223], s[42:43], 0, v[130:131]
	s_mov_b32 m0, s37
	s_nop 0
	global_load_lds_dwordx4 v[222:223], off
	s_mov_b32 m0, s47
	s_nop 0
	global_load_lds_dwordx4 v[224:225], off
	s_waitcnt vmcnt(8)
	s_waitcnt lgkmcnt(0)
	s_barrier
	s_setprio 1
	s_waitcnt lgkmcnt(0)
	v_mfma_f32_16x16x32_bf16 v[62:65], v[154:157], v[190:193], v[62:65]
	v_mfma_f32_16x16x32_bf16 v[58:61], v[162:165], v[190:193], v[58:61]
	v_mfma_f32_16x16x32_bf16 v[54:57], v[154:157], v[198:201], v[54:57]
	v_mfma_f32_16x16x32_bf16 v[46:49], v[162:165], v[198:201], v[46:49]
	v_mfma_f32_16x16x32_bf16 v[38:41], v[154:157], v[206:209], v[38:41]
	v_mfma_f32_16x16x32_bf16 v[30:33], v[162:165], v[206:209], v[30:33]
	v_mfma_f32_16x16x32_bf16 v[22:25], v[154:157], v[214:217], v[22:25]
	v_mfma_f32_16x16x32_bf16 v[14:17], v[162:165], v[214:217], v[14:17]
	v_mfma_f32_16x16x32_bf16 v[62:65], v[158:161], v[194:197], v[62:65]
	v_mfma_f32_16x16x32_bf16 v[58:61], v[166:169], v[194:197], v[58:61]
	v_mfma_f32_16x16x32_bf16 v[54:57], v[158:161], v[202:205], v[54:57]
	v_mfma_f32_16x16x32_bf16 v[46:49], v[166:169], v[202:205], v[46:49]
	v_mfma_f32_16x16x32_bf16 v[38:41], v[158:161], v[210:213], v[38:41]
	v_mfma_f32_16x16x32_bf16 v[30:33], v[166:169], v[210:213], v[30:33]
	v_mfma_f32_16x16x32_bf16 v[22:25], v[158:161], v[218:221], v[22:25]
	v_mfma_f32_16x16x32_bf16 v[14:17], v[166:169], v[218:221], v[14:17]
	v_mfma_f32_16x16x32_bf16 v[50:53], v[170:173], v[190:193], v[50:53]
	v_mfma_f32_16x16x32_bf16 v[42:45], v[178:181], v[190:193], v[42:45]
	v_mfma_f32_16x16x32_bf16 v[34:37], v[170:173], v[198:201], v[34:37]
	v_mfma_f32_16x16x32_bf16 v[26:29], v[178:181], v[198:201], v[26:29]
	v_mfma_f32_16x16x32_bf16 v[18:21], v[170:173], v[206:209], v[18:21]
	v_mfma_f32_16x16x32_bf16 v[10:13], v[178:181], v[206:209], v[10:13]
	v_mfma_f32_16x16x32_bf16 v[6:9], v[170:173], v[214:217], v[6:9]
	v_mfma_f32_16x16x32_bf16 v[2:5], v[178:181], v[214:217], v[2:5]
	v_mfma_f32_16x16x32_bf16 v[50:53], v[174:177], v[194:197], v[50:53]
	v_mfma_f32_16x16x32_bf16 v[42:45], v[186:189], v[194:197], v[42:45]
	v_mfma_f32_16x16x32_bf16 v[34:37], v[174:177], v[202:205], v[34:37]
	v_mfma_f32_16x16x32_bf16 v[26:29], v[186:189], v[202:205], v[26:29]
	v_mfma_f32_16x16x32_bf16 v[18:21], v[174:177], v[210:213], v[18:21]
	v_mfma_f32_16x16x32_bf16 v[10:13], v[186:189], v[210:213], v[10:13]
	v_mfma_f32_16x16x32_bf16 v[6:9], v[174:177], v[218:221], v[6:9]
	v_mfma_f32_16x16x32_bf16 v[2:5], v[186:189], v[218:221], v[2:5]
	s_setprio 0
	s_barrier
	s_add_i32 s54, 0, 0x18000
	v_add_u32_e32 v153, s54, v148
	s_add_i32 s55, 0, 0x1c000
	ds_read_b128 v[154:157], v153
	ds_read_b128 v[158:161], v153 offset:1024
	ds_read_b128 v[162:165], v153 offset:2048
	ds_read_b128 v[166:169], v153 offset:3072
	v_add_u32_e32 v153, s55, v148
	ds_read_b128 v[170:173], v153
	ds_read_b128 v[174:177], v153 offset:1024
	ds_read_b128 v[178:181], v153 offset:2048
	ds_read_b128 v[186:189], v153 offset:3072
	s_add_u32 s42, s42, 0x40000
	s_addc_u32 s43, s43, 0
	s_mov_b32 m0, s48
	v_lshl_add_u64 v[226:227], s[42:43], 0, v[130:131]
	ds_read_b128 v[190:193], v152 offset:32768
	ds_read_b128 v[194:197], v152 offset:33792
	ds_read_b128 v[198:201], v152 offset:34816
	ds_read_b128 v[202:205], v152 offset:35840
	ds_read_b128 v[206:209], v152 offset:36864
	ds_read_b128 v[210:213], v152 offset:37888
	ds_read_b128 v[214:217], v152 offset:38912
	ds_read_b128 v[218:221], v152 offset:39936
	global_load_lds_dwordx4 v[226:227], off
	v_lshl_add_u64 v[226:227], s[42:43], 0, v[134:135]
	s_mov_b32 m0, s49
	s_nop 0
	global_load_lds_dwordx4 v[226:227], off
	s_waitcnt vmcnt(8)
	s_waitcnt lgkmcnt(0)
	s_barrier
	s_setprio 1
	s_waitcnt lgkmcnt(0)
	v_mfma_f32_16x16x32_bf16 v[126:129], v[154:157], v[190:193], v[126:129]
	v_mfma_f32_16x16x32_bf16 v[122:125], v[162:165], v[190:193], v[122:125]
	v_mfma_f32_16x16x32_bf16 v[118:121], v[154:157], v[198:201], v[118:121]
	v_mfma_f32_16x16x32_bf16 v[110:113], v[162:165], v[198:201], v[110:113]
	v_mfma_f32_16x16x32_bf16 v[102:105], v[154:157], v[206:209], v[102:105]
	v_mfma_f32_16x16x32_bf16 v[94:97], v[162:165], v[206:209], v[94:97]
	v_mfma_f32_16x16x32_bf16 v[86:89], v[154:157], v[214:217], v[86:89]
	v_mfma_f32_16x16x32_bf16 v[78:81], v[162:165], v[214:217], v[78:81]
	v_mfma_f32_16x16x32_bf16 v[126:129], v[158:161], v[194:197], v[126:129]
	v_mfma_f32_16x16x32_bf16 v[122:125], v[166:169], v[194:197], v[122:125]
	v_mfma_f32_16x16x32_bf16 v[118:121], v[158:161], v[202:205], v[118:121]
	v_mfma_f32_16x16x32_bf16 v[110:113], v[166:169], v[202:205], v[110:113]
	v_mfma_f32_16x16x32_bf16 v[102:105], v[158:161], v[210:213], v[102:105]
	v_mfma_f32_16x16x32_bf16 v[94:97], v[166:169], v[210:213], v[94:97]
	v_mfma_f32_16x16x32_bf16 v[86:89], v[158:161], v[218:221], v[86:89]
	v_mfma_f32_16x16x32_bf16 v[78:81], v[166:169], v[218:221], v[78:81]
	v_mfma_f32_16x16x32_bf16 v[114:117], v[170:173], v[190:193], v[114:117]
	v_mfma_f32_16x16x32_bf16 v[106:109], v[178:181], v[190:193], v[106:109]
	v_mfma_f32_16x16x32_bf16 v[98:101], v[170:173], v[198:201], v[98:101]
	v_mfma_f32_16x16x32_bf16 v[90:93], v[178:181], v[198:201], v[90:93]
	v_mfma_f32_16x16x32_bf16 v[82:85], v[170:173], v[206:209], v[82:85]
	v_mfma_f32_16x16x32_bf16 v[74:77], v[178:181], v[206:209], v[74:77]
	v_mfma_f32_16x16x32_bf16 v[70:73], v[170:173], v[214:217], v[70:73]
	v_mfma_f32_16x16x32_bf16 v[66:69], v[178:181], v[214:217], v[66:69]
	v_mfma_f32_16x16x32_bf16 v[114:117], v[174:177], v[194:197], v[114:117]
	v_mfma_f32_16x16x32_bf16 v[106:109], v[186:189], v[194:197], v[106:109]
	v_mfma_f32_16x16x32_bf16 v[98:101], v[174:177], v[202:205], v[98:101]
	v_mfma_f32_16x16x32_bf16 v[90:93], v[186:189], v[202:205], v[90:93]
	v_mfma_f32_16x16x32_bf16 v[82:85], v[174:177], v[210:213], v[82:85]
	v_mfma_f32_16x16x32_bf16 v[74:77], v[186:189], v[210:213], v[74:77]
	v_mfma_f32_16x16x32_bf16 v[70:73], v[174:177], v[218:221], v[70:73]
	v_mfma_f32_16x16x32_bf16 v[66:69], v[186:189], v[218:221], v[66:69]
	s_setprio 0
	s_barrier
	s_add_i32 s42, s54, s45
	v_lshl_add_u64 v[146:147], v[146:147], 0, s[14:15]
	s_mov_b32 m0, s42
	ds_read_b128 v[190:193], v152 offset:49152
	ds_read_b128 v[194:197], v152 offset:50176
	ds_read_b128 v[198:201], v152 offset:51200
	ds_read_b128 v[202:205], v152 offset:52224
	ds_read_b128 v[206:209], v152 offset:53248
	ds_read_b128 v[210:213], v152 offset:54272
	ds_read_b128 v[214:217], v152 offset:55296
	ds_read_b128 v[218:221], v152 offset:56320
	global_load_lds_dwordx4 v[146:147], off
	s_add_i32 m0, s42, 0x2000
	s_add_u32 s40, s40, 0x40080
	v_lshl_add_u64 v[146:147], v[182:183], 0, s[14:15]
	s_addc_u32 s41, s41, 0
	s_add_i32 s42, s55, s45
	global_load_lds_dwordx4 v[146:147], off
	v_lshl_add_u64 v[146:147], s[40:41], 0, v[132:133]
	s_mov_b32 m0, s42
	s_nop 0
	global_load_lds_dwordx4 v[146:147], off
	v_lshl_add_u64 v[146:147], s[40:41], 0, v[136:137]
	s_add_i32 m0, s42, 0x2000
	s_nop 0
	global_load_lds_dwordx4 v[146:147], off
	v_lshl_add_u64 v[146:147], v[222:223], 0, s[14:15]
	s_mov_b32 m0, s58
	s_nop 0
	global_load_lds_dwordx4 v[146:147], off
	v_lshl_add_u64 v[146:147], v[224:225], 0, s[14:15]
	s_mov_b32 m0, s59
	s_nop 0
	global_load_lds_dwordx4 v[146:147], off
	s_waitcnt vmcnt(8)
	s_waitcnt lgkmcnt(0)
	s_barrier
	s_setprio 1
	s_waitcnt lgkmcnt(0)
	v_mfma_f32_16x16x32_bf16 v[62:65], v[154:157], v[190:193], v[62:65]
	v_mfma_f32_16x16x32_bf16 v[58:61], v[162:165], v[190:193], v[58:61]
	v_mfma_f32_16x16x32_bf16 v[54:57], v[154:157], v[198:201], v[54:57]
	v_mfma_f32_16x16x32_bf16 v[46:49], v[162:165], v[198:201], v[46:49]
	v_mfma_f32_16x16x32_bf16 v[38:41], v[154:157], v[206:209], v[38:41]
	v_mfma_f32_16x16x32_bf16 v[30:33], v[162:165], v[206:209], v[30:33]
	v_mfma_f32_16x16x32_bf16 v[22:25], v[154:157], v[214:217], v[22:25]
	v_mfma_f32_16x16x32_bf16 v[14:17], v[162:165], v[214:217], v[14:17]
	v_mfma_f32_16x16x32_bf16 v[62:65], v[158:161], v[194:197], v[62:65]
	v_mfma_f32_16x16x32_bf16 v[58:61], v[166:169], v[194:197], v[58:61]
	v_mfma_f32_16x16x32_bf16 v[54:57], v[158:161], v[202:205], v[54:57]
	v_mfma_f32_16x16x32_bf16 v[46:49], v[166:169], v[202:205], v[46:49]
	v_mfma_f32_16x16x32_bf16 v[38:41], v[158:161], v[210:213], v[38:41]
	v_mfma_f32_16x16x32_bf16 v[30:33], v[166:169], v[210:213], v[30:33]
	v_mfma_f32_16x16x32_bf16 v[22:25], v[158:161], v[218:221], v[22:25]
	v_mfma_f32_16x16x32_bf16 v[14:17], v[166:169], v[218:221], v[14:17]
	v_mfma_f32_16x16x32_bf16 v[50:53], v[170:173], v[190:193], v[50:53]
	v_mfma_f32_16x16x32_bf16 v[42:45], v[178:181], v[190:193], v[42:45]
	v_mfma_f32_16x16x32_bf16 v[34:37], v[170:173], v[198:201], v[34:37]
	v_mfma_f32_16x16x32_bf16 v[26:29], v[178:181], v[198:201], v[26:29]
	v_mfma_f32_16x16x32_bf16 v[18:21], v[170:173], v[206:209], v[18:21]
	v_mfma_f32_16x16x32_bf16 v[10:13], v[178:181], v[206:209], v[10:13]
	v_mfma_f32_16x16x32_bf16 v[6:9], v[170:173], v[214:217], v[6:9]
	v_mfma_f32_16x16x32_bf16 v[2:5], v[178:181], v[214:217], v[2:5]
	v_mfma_f32_16x16x32_bf16 v[50:53], v[174:177], v[194:197], v[50:53]
	v_mfma_f32_16x16x32_bf16 v[42:45], v[186:189], v[194:197], v[42:45]
	v_mfma_f32_16x16x32_bf16 v[34:37], v[174:177], v[202:205], v[34:37]
	v_mfma_f32_16x16x32_bf16 v[26:29], v[186:189], v[202:205], v[26:29]
	v_mfma_f32_16x16x32_bf16 v[18:21], v[174:177], v[210:213], v[18:21]
	v_mfma_f32_16x16x32_bf16 v[10:13], v[186:189], v[210:213], v[10:13]
	v_mfma_f32_16x16x32_bf16 v[6:9], v[174:177], v[218:221], v[6:9]
	v_mfma_f32_16x16x32_bf16 v[2:5], v[186:189], v[218:221], v[2:5]
	s_setprio 0
	s_barrier
	s_add_i32 s74, s74, 2
	s_add_u32 s72, s72, 0x100
	s_addc_u32 s73, s73, 0
	s_add_u32 s38, s38, 0x100
	s_addc_u32 s39, s39, 0
	s_cmp_gt_u32 s74, 13
	s_cbranch_scc0 .LBB0_647
	v_lshl_add_u32 v154, s36, 8, v1
	v_lshl_or_b32 v146, s67, 8, v149
	v_ashrrev_i32_e32 v155, 31, v154
	v_ashrrev_i32_e32 v147, 31, v146
	v_lshlrev_b64 v[156:157], 11, v[154:155]
	v_lshl_add_u64 v[156:157], s[6:7], 0, v[156:157]
	v_lshlrev_b64 v[158:159], 1, v[146:147]
	v_lshl_add_u64 v[146:147], v[156:157], 0, v[158:159]
	v_cvt_pk_bf16_f32 v126, v126, v127
	v_cvt_pk_bf16_f32 v127, v128, v129
	v_cvt_pk_bf16_f32 v128, v122, v123
	v_cvt_pk_bf16_f32 v129, v124, v125
	global_store_dwordx4 v[146:147], v[126:129], off
	v_cvt_pk_bf16_f32 v114, v114, v115
	v_cvt_pk_bf16_f32 v115, v116, v117
	v_cvt_pk_bf16_f32 v116, v106, v107
	v_or_b32_e32 v106, 16, v154
	v_ashrrev_i32_e32 v107, 31, v106
	v_lshlrev_b64 v[106:107], 11, v[106:107]
	v_lshl_add_u64 v[106:107], s[6:7], 0, v[106:107]
	v_cvt_pk_bf16_f32 v117, v108, v109
	global_store_dwordx4 v[146:147], v[114:117], off offset:256
	s_mov_b32 s67, s24
	s_mov_b32 s36, s26
	v_lshl_add_u64 v[114:115], v[106:107], 0, v[158:159]
	v_cvt_pk_bf16_f32 v106, v118, v119
	v_cvt_pk_bf16_f32 v107, v120, v121
	v_cvt_pk_bf16_f32 v108, v110, v111
	v_cvt_pk_bf16_f32 v109, v112, v113
	global_store_dwordx4 v[114:115], v[106:109], off
	v_cvt_pk_bf16_f32 v98, v98, v99
	v_cvt_pk_bf16_f32 v99, v100, v101
	v_cvt_pk_bf16_f32 v100, v90, v91
	v_or_b32_e32 v90, 32, v154
	v_ashrrev_i32_e32 v91, 31, v90
	v_lshlrev_b64 v[90:91], 11, v[90:91]
	v_lshl_add_u64 v[90:91], s[6:7], 0, v[90:91]
	v_cvt_pk_bf16_f32 v101, v92, v93
	global_store_dwordx4 v[114:115], v[98:101], off offset:256
	s_mov_b64 s[38:39], s[30:31]
	s_mov_b64 s[40:41], s[28:29]
	v_lshl_add_u64 v[98:99], v[90:91], 0, v[158:159]
	v_cvt_pk_bf16_f32 v90, v102, v103
	v_cvt_pk_bf16_f32 v91, v104, v105
	v_cvt_pk_bf16_f32 v92, v94, v95
	v_cvt_pk_bf16_f32 v93, v96, v97
	global_store_dwordx4 v[98:99], v[90:93], off
	v_cvt_pk_bf16_f32 v82, v82, v83
	v_cvt_pk_bf16_f32 v83, v84, v85
	v_cvt_pk_bf16_f32 v84, v74, v75
	v_or_b32_e32 v74, 48, v154
	v_ashrrev_i32_e32 v75, 31, v74
	v_lshlrev_b64 v[74:75], 11, v[74:75]
	v_lshl_add_u64 v[74:75], s[6:7], 0, v[74:75]
	v_cvt_pk_bf16_f32 v85, v76, v77
	global_store_dwordx4 v[98:99], v[82:85], off offset:256
	s_nop 1
	v_lshl_add_u64 v[82:83], v[74:75], 0, v[158:159]
	v_cvt_pk_bf16_f32 v74, v86, v87
	v_cvt_pk_bf16_f32 v75, v88, v89
	v_cvt_pk_bf16_f32 v76, v78, v79
	v_cvt_pk_bf16_f32 v77, v80, v81
	global_store_dwordx4 v[82:83], v[74:77], off
	v_cvt_pk_bf16_f32 v70, v70, v71
	v_cvt_pk_bf16_f32 v71, v72, v73
	v_cvt_pk_bf16_f32 v72, v66, v67
	v_cvt_pk_bf16_f32 v73, v68, v69
	global_store_dwordx4 v[82:83], v[70:73], off offset:256
	v_cvt_pk_bf16_f32 v62, v62, v63
	v_cvt_pk_bf16_f32 v63, v64, v65
	v_cvt_pk_bf16_f32 v64, v58, v59
	v_add_co_u32_e32 v58, vcc, s62, v146
	v_lshl_add_u64 v[66:67], v[146:147], 0, s[12:13]
	s_nop 0
	v_addc_co_u32_e32 v59, vcc, 0, v147, vcc
	v_cvt_pk_bf16_f32 v65, v60, v61
	global_store_dwordx4 v[58:59], v[62:65], off
	v_cvt_pk_bf16_f32 v50, v50, v51
	v_cvt_pk_bf16_f32 v51, v52, v53
	v_cvt_pk_bf16_f32 v52, v42, v43
	v_cvt_pk_bf16_f32 v53, v44, v45
	global_store_dwordx4 v[66:67], v[50:53], off offset:256
	v_cvt_pk_bf16_f32 v42, v54, v55
	v_cvt_pk_bf16_f32 v43, v56, v57
	v_cvt_pk_bf16_f32 v44, v46, v47
	v_add_co_u32_e32 v46, vcc, s63, v146
	s_nop 0
	v_lshl_add_u64 v[50:51], v[146:147], 0, s[16:17]
	v_addc_co_u32_e32 v47, vcc, 0, v147, vcc
	v_cvt_pk_bf16_f32 v45, v48, v49
	global_store_dwordx4 v[46:47], v[42:45], off
	v_cvt_pk_bf16_f32 v34, v34, v35
	v_cvt_pk_bf16_f32 v35, v36, v37
	v_cvt_pk_bf16_f32 v36, v26, v27
	v_cvt_pk_bf16_f32 v37, v28, v29
	global_store_dwordx4 v[50:51], v[34:37], off offset:256
	v_cvt_pk_bf16_f32 v26, v38, v39
	v_cvt_pk_bf16_f32 v27, v40, v41
	v_cvt_pk_bf16_f32 v28, v30, v31
	v_add_co_u32_e32 v30, vcc, s64, v146
	s_nop 0
	v_lshl_add_u64 v[34:35], v[146:147], 0, s[18:19]
	v_addc_co_u32_e32 v31, vcc, 0, v147, vcc
	v_cvt_pk_bf16_f32 v29, v32, v33
	global_store_dwordx4 v[30:31], v[26:29], off
	v_cvt_pk_bf16_f32 v18, v18, v19
	v_cvt_pk_bf16_f32 v19, v20, v21
	v_cvt_pk_bf16_f32 v20, v10, v11
	v_cvt_pk_bf16_f32 v21, v12, v13
	global_store_dwordx4 v[34:35], v[18:21], off offset:256
	v_cvt_pk_bf16_f32 v10, v22, v23
	v_cvt_pk_bf16_f32 v11, v24, v25
	v_cvt_pk_bf16_f32 v12, v14, v15
	v_add_co_u32_e32 v14, vcc, s66, v146
	s_nop 0
	v_lshl_add_u64 v[18:19], v[146:147], 0, s[20:21]
	v_addc_co_u32_e32 v15, vcc, 0, v147, vcc
	s_and_b64 vcc, exec, s[4:5]
	v_cvt_pk_bf16_f32 v13, v16, v17
	global_store_dwordx4 v[14:15], v[10:13], off
	v_cvt_pk_bf16_f32 v6, v6, v7
	v_cvt_pk_bf16_f32 v7, v8, v9
	v_cvt_pk_bf16_f32 v8, v2, v3
	v_cvt_pk_bf16_f32 v9, v4, v5
	global_store_dwordx4 v[18:19], v[6:9], off offset:256
	s_cbranch_vccz .LBB0_640
	s_waitcnt vmcnt(0)
	s_cmpk_gt_u32 s44, 0xff
	s_cbranch_scc1 .LBB0_651
	s_barrier

.LBB0_814:
	ds_read_b128 v[148:151], v155
	ds_read_b128 v[158:161], v155 offset:1024
	ds_read_b128 v[162:165], v155 offset:2048
	ds_read_b128 v[166:169], v155 offset:3072
	ds_read_b128 v[170:173], v156
	ds_read_b128 v[174:177], v156 offset:1024
	ds_read_b128 v[178:181], v156 offset:2048
	ds_read_b128 v[186:189], v156 offset:3072
	s_add_u32 s42, s40, 0xfffc0080
	s_addc_u32 s43, s41, -1
	s_cmp_eq_u32 s73, 12
	s_cselect_b32 s45, s7, s43
	s_cselect_b32 s44, s29, s42
	s_cselect_b32 s43, s27, s72
	s_cselect_b32 s42, s68, s69
	v_lshl_add_u64 v[152:153], s[40:41], 0, v[140:141]
	s_add_i32 m0, s39, 0xc000
	ds_read_b128 v[190:193], v157
	ds_read_b128 v[194:197], v157 offset:1024
	ds_read_b128 v[198:201], v157 offset:2048
	ds_read_b128 v[202:205], v157 offset:3072
	ds_read_b128 v[206:209], v157 offset:4096
	ds_read_b128 v[210:213], v157 offset:5120
	ds_read_b128 v[214:217], v157 offset:6144
	ds_read_b128 v[218:221], v157 offset:7168
	global_load_lds_dwordx4 v[152:153], off
	v_lshl_add_u64 v[152:153], s[40:41], 0, v[142:143]
	s_add_i32 m0, s39, 0xe000
	s_nop 0
	global_load_lds_dwordx4 v[152:153], off
	s_waitcnt vmcnt(8)
	s_waitcnt lgkmcnt(0)
	s_barrier
	s_setprio 1
	s_waitcnt lgkmcnt(0)
	v_mfma_f32_16x16x32_bf16 v[126:129], v[148:151], v[190:193], v[126:129]
	v_mfma_f32_16x16x32_bf16 v[122:125], v[162:165], v[190:193], v[122:125]
	v_mfma_f32_16x16x32_bf16 v[110:113], v[148:151], v[198:201], v[110:113]
	v_mfma_f32_16x16x32_bf16 v[106:109], v[162:165], v[198:201], v[106:109]
	v_mfma_f32_16x16x32_bf16 v[94:97], v[148:151], v[206:209], v[94:97]
	v_mfma_f32_16x16x32_bf16 v[90:93], v[162:165], v[206:209], v[90:93]
	v_mfma_f32_16x16x32_bf16 v[78:81], v[148:151], v[214:217], v[78:81]
	v_mfma_f32_16x16x32_bf16 v[74:77], v[162:165], v[214:217], v[74:77]
	v_mfma_f32_16x16x32_bf16 v[126:129], v[158:161], v[194:197], v[126:129]
	v_mfma_f32_16x16x32_bf16 v[122:125], v[166:169], v[194:197], v[122:125]
	v_mfma_f32_16x16x32_bf16 v[110:113], v[158:161], v[202:205], v[110:113]
	v_mfma_f32_16x16x32_bf16 v[106:109], v[166:169], v[202:205], v[106:109]
	v_mfma_f32_16x16x32_bf16 v[94:97], v[158:161], v[210:213], v[94:97]
	v_mfma_f32_16x16x32_bf16 v[90:93], v[166:169], v[210:213], v[90:93]
	v_mfma_f32_16x16x32_bf16 v[78:81], v[158:161], v[218:221], v[78:81]
	v_mfma_f32_16x16x32_bf16 v[74:77], v[166:169], v[218:221], v[74:77]
	v_mfma_f32_16x16x32_bf16 v[118:121], v[170:173], v[190:193], v[118:121]
	v_mfma_f32_16x16x32_bf16 v[114:117], v[178:181], v[190:193], v[114:117]
	v_mfma_f32_16x16x32_bf16 v[102:105], v[170:173], v[198:201], v[102:105]
	v_mfma_f32_16x16x32_bf16 v[98:101], v[178:181], v[198:201], v[98:101]
	v_mfma_f32_16x16x32_bf16 v[86:89], v[170:173], v[206:209], v[86:89]
	v_mfma_f32_16x16x32_bf16 v[82:85], v[178:181], v[206:209], v[82:85]
	v_mfma_f32_16x16x32_bf16 v[70:73], v[170:173], v[214:217], v[70:73]
	v_mfma_f32_16x16x32_bf16 v[66:69], v[178:181], v[214:217], v[66:69]
	v_mfma_f32_16x16x32_bf16 v[118:121], v[174:177], v[194:197], v[118:121]
	v_mfma_f32_16x16x32_bf16 v[114:117], v[186:189], v[194:197], v[114:117]
	v_mfma_f32_16x16x32_bf16 v[102:105], v[174:177], v[202:205], v[102:105]
	v_mfma_f32_16x16x32_bf16 v[98:101], v[186:189], v[202:205], v[98:101]
	v_mfma_f32_16x16x32_bf16 v[86:89], v[174:177], v[210:213], v[86:89]
	v_mfma_f32_16x16x32_bf16 v[82:85], v[186:189], v[210:213], v[82:85]
	v_mfma_f32_16x16x32_bf16 v[70:73], v[174:177], v[218:221], v[70:73]
	v_mfma_f32_16x16x32_bf16 v[66:69], v[186:189], v[218:221], v[66:69]
	s_setprio 0
	s_barrier
	s_add_i32 s54, s63, s47
	v_lshl_add_u64 v[152:153], s[42:43], 0, v[132:133]
	s_mov_b32 m0, s54
	ds_read_b128 v[190:193], v157 offset:16384
	ds_read_b128 v[194:197], v157 offset:17408
	ds_read_b128 v[198:201], v157 offset:18432
	ds_read_b128 v[202:205], v157 offset:19456
	ds_read_b128 v[206:209], v157 offset:20480
	ds_read_b128 v[210:213], v157 offset:21504
	ds_read_b128 v[214:217], v157 offset:22528
	ds_read_b128 v[218:221], v157 offset:23552
	global_load_lds_dwordx4 v[152:153], off
	s_add_i32 m0, s54, 0x2000
	s_add_u32 s54, s42, 0x40000
	v_lshl_add_u64 v[182:183], s[42:43], 0, v[136:137]
	s_addc_u32 s55, s43, 0
	s_add_i32 s56, s64, s47
	global_load_lds_dwordx4 v[182:183], off
	v_lshl_add_u64 v[222:223], s[54:55], 0, v[132:133]
	s_mov_b32 m0, s56
	v_lshl_add_u64 v[224:225], s[44:45], 0, v[134:135]
	global_load_lds_dwordx4 v[222:223], off
	v_lshl_add_u64 v[222:223], s[54:55], 0, v[136:137]
	s_add_i32 m0, s56, 0x2000
	s_nop 0
	global_load_lds_dwordx4 v[222:223], off
	v_lshl_add_u64 v[222:223], s[44:45], 0, v[130:131]
	s_mov_b32 m0, s39
	s_nop 0
	global_load_lds_dwordx4 v[222:223], off
	s_mov_b32 m0, s48
	s_nop 0
	global_load_lds_dwordx4 v[224:225], off
	s_waitcnt vmcnt(8)
	s_waitcnt lgkmcnt(0)
	s_barrier
	s_setprio 1
	s_waitcnt lgkmcnt(0)
	v_mfma_f32_16x16x32_bf16 v[62:65], v[148:151], v[190:193], v[62:65]
	v_mfma_f32_16x16x32_bf16 v[58:61], v[162:165], v[190:193], v[58:61]
	v_mfma_f32_16x16x32_bf16 v[46:49], v[148:151], v[198:201], v[46:49]
	v_mfma_f32_16x16x32_bf16 v[42:45], v[162:165], v[198:201], v[42:45]
	v_mfma_f32_16x16x32_bf16 v[30:33], v[148:151], v[206:209], v[30:33]
	v_mfma_f32_16x16x32_bf16 v[26:29], v[162:165], v[206:209], v[26:29]
	v_mfma_f32_16x16x32_bf16 v[14:17], v[148:151], v[214:217], v[14:17]
	v_mfma_f32_16x16x32_bf16 v[10:13], v[162:165], v[214:217], v[10:13]
	v_mfma_f32_16x16x32_bf16 v[62:65], v[158:161], v[194:197], v[62:65]
	v_mfma_f32_16x16x32_bf16 v[58:61], v[166:169], v[194:197], v[58:61]
	v_mfma_f32_16x16x32_bf16 v[46:49], v[158:161], v[202:205], v[46:49]
	v_mfma_f32_16x16x32_bf16 v[42:45], v[166:169], v[202:205], v[42:45]
	v_mfma_f32_16x16x32_bf16 v[30:33], v[158:161], v[210:213], v[30:33]
	v_mfma_f32_16x16x32_bf16 v[26:29], v[166:169], v[210:213], v[26:29]
	v_mfma_f32_16x16x32_bf16 v[14:17], v[158:161], v[218:221], v[14:17]
	v_mfma_f32_16x16x32_bf16 v[10:13], v[166:169], v[218:221], v[10:13]
	v_mfma_f32_16x16x32_bf16 v[54:57], v[170:173], v[190:193], v[54:57]
	v_mfma_f32_16x16x32_bf16 v[50:53], v[178:181], v[190:193], v[50:53]
	v_mfma_f32_16x16x32_bf16 v[38:41], v[170:173], v[198:201], v[38:41]
	v_mfma_f32_16x16x32_bf16 v[34:37], v[178:181], v[198:201], v[34:37]
	v_mfma_f32_16x16x32_bf16 v[22:25], v[170:173], v[206:209], v[22:25]
	v_mfma_f32_16x16x32_bf16 v[18:21], v[178:181], v[206:209], v[18:21]
	v_mfma_f32_16x16x32_bf16 v[6:9], v[170:173], v[214:217], v[6:9]
	v_mfma_f32_16x16x32_bf16 v[2:5], v[178:181], v[214:217], v[2:5]
	v_mfma_f32_16x16x32_bf16 v[54:57], v[174:177], v[194:197], v[54:57]
	v_mfma_f32_16x16x32_bf16 v[50:53], v[186:189], v[194:197], v[50:53]
	v_mfma_f32_16x16x32_bf16 v[38:41], v[174:177], v[202:205], v[38:41]
	v_mfma_f32_16x16x32_bf16 v[34:37], v[186:189], v[202:205], v[34:37]
	v_mfma_f32_16x16x32_bf16 v[22:25], v[174:177], v[210:213], v[22:25]
	v_mfma_f32_16x16x32_bf16 v[18:21], v[186:189], v[210:213], v[18:21]
	v_mfma_f32_16x16x32_bf16 v[6:9], v[174:177], v[218:221], v[6:9]
	v_mfma_f32_16x16x32_bf16 v[2:5], v[186:189], v[218:221], v[2:5]
	s_setprio 0
	s_barrier
	s_add_i32 s54, 0, 0x18000
	s_add_i32 s55, 0, 0x1c000
	v_add_u32_e32 v166, s54, v154
	v_add_u32_e32 v185, s55, v154
	ds_read_b128 v[148:151], v166
	ds_read_b128 v[158:161], v166 offset:1024
	ds_read_b128 v[162:165], v166 offset:2048
	ds_read_b128 v[166:169], v166 offset:3072
	ds_read_b128 v[170:173], v185
	ds_read_b128 v[174:177], v185 offset:1024
	ds_read_b128 v[178:181], v185 offset:2048
	ds_read_b128 v[186:189], v185 offset:3072
	s_add_u32 s44, s44, 0x40000
	s_addc_u32 s45, s45, 0
	s_mov_b32 m0, s49
	v_lshl_add_u64 v[226:227], s[44:45], 0, v[130:131]
	ds_read_b128 v[190:193], v157 offset:32768
	ds_read_b128 v[194:197], v157 offset:33792
	ds_read_b128 v[198:201], v157 offset:34816
	ds_read_b128 v[202:205], v157 offset:35840
	ds_read_b128 v[206:209], v157 offset:36864
	ds_read_b128 v[210:213], v157 offset:37888
	ds_read_b128 v[214:217], v157 offset:38912
	ds_read_b128 v[218:221], v157 offset:39936
	global_load_lds_dwordx4 v[226:227], off
	v_lshl_add_u64 v[226:227], s[44:45], 0, v[134:135]
	s_mov_b32 m0, s50
	s_nop 0
	global_load_lds_dwordx4 v[226:227], off
	s_waitcnt vmcnt(8)
	s_waitcnt lgkmcnt(0)
	s_barrier
	s_setprio 1
	s_waitcnt lgkmcnt(0)
	v_mfma_f32_16x16x32_bf16 v[126:129], v[148:151], v[190:193], v[126:129]
	v_mfma_f32_16x16x32_bf16 v[122:125], v[162:165], v[190:193], v[122:125]
	v_mfma_f32_16x16x32_bf16 v[110:113], v[148:151], v[198:201], v[110:113]
	v_mfma_f32_16x16x32_bf16 v[106:109], v[162:165], v[198:201], v[106:109]
	v_mfma_f32_16x16x32_bf16 v[94:97], v[148:151], v[206:209], v[94:97]
	v_mfma_f32_16x16x32_bf16 v[90:93], v[162:165], v[206:209], v[90:93]
	v_mfma_f32_16x16x32_bf16 v[78:81], v[148:151], v[214:217], v[78:81]
	v_mfma_f32_16x16x32_bf16 v[74:77], v[162:165], v[214:217], v[74:77]
	v_mfma_f32_16x16x32_bf16 v[126:129], v[158:161], v[194:197], v[126:129]
	v_mfma_f32_16x16x32_bf16 v[122:125], v[166:169], v[194:197], v[122:125]
	v_mfma_f32_16x16x32_bf16 v[110:113], v[158:161], v[202:205], v[110:113]
	v_mfma_f32_16x16x32_bf16 v[106:109], v[166:169], v[202:205], v[106:109]
	v_mfma_f32_16x16x32_bf16 v[94:97], v[158:161], v[210:213], v[94:97]
	v_mfma_f32_16x16x32_bf16 v[90:93], v[166:169], v[210:213], v[90:93]
	v_mfma_f32_16x16x32_bf16 v[78:81], v[158:161], v[218:221], v[78:81]
	v_mfma_f32_16x16x32_bf16 v[74:77], v[166:169], v[218:221], v[74:77]
	v_mfma_f32_16x16x32_bf16 v[118:121], v[170:173], v[190:193], v[118:121]
	v_mfma_f32_16x16x32_bf16 v[114:117], v[178:181], v[190:193], v[114:117]
	v_mfma_f32_16x16x32_bf16 v[102:105], v[170:173], v[198:201], v[102:105]
	v_mfma_f32_16x16x32_bf16 v[98:101], v[178:181], v[198:201], v[98:101]
	v_mfma_f32_16x16x32_bf16 v[86:89], v[170:173], v[206:209], v[86:89]
	v_mfma_f32_16x16x32_bf16 v[82:85], v[178:181], v[206:209], v[82:85]
	v_mfma_f32_16x16x32_bf16 v[70:73], v[170:173], v[214:217], v[70:73]
	v_mfma_f32_16x16x32_bf16 v[66:69], v[178:181], v[214:217], v[66:69]
	v_mfma_f32_16x16x32_bf16 v[118:121], v[174:177], v[194:197], v[118:121]
	v_mfma_f32_16x16x32_bf16 v[114:117], v[186:189], v[194:197], v[114:117]
	v_mfma_f32_16x16x32_bf16 v[102:105], v[174:177], v[202:205], v[102:105]
	v_mfma_f32_16x16x32_bf16 v[98:101], v[186:189], v[202:205], v[98:101]
	v_mfma_f32_16x16x32_bf16 v[86:89], v[174:177], v[210:213], v[86:89]
	v_mfma_f32_16x16x32_bf16 v[82:85], v[186:189], v[210:213], v[82:85]
	v_mfma_f32_16x16x32_bf16 v[70:73], v[174:177], v[218:221], v[70:73]
	v_mfma_f32_16x16x32_bf16 v[66:69], v[186:189], v[218:221], v[66:69]
	s_setprio 0
	s_barrier
	s_add_i32 s44, s54, s47
	v_lshl_add_u64 v[152:153], v[152:153], 0, s[14:15]
	s_mov_b32 m0, s44
	ds_read_b128 v[190:193], v157 offset:49152
	ds_read_b128 v[194:197], v157 offset:50176
	ds_read_b128 v[198:201], v157 offset:51200
	ds_read_b128 v[202:205], v157 offset:52224
	ds_read_b128 v[206:209], v157 offset:53248
	ds_read_b128 v[210:213], v157 offset:54272
	ds_read_b128 v[214:217], v157 offset:55296
	ds_read_b128 v[218:221], v157 offset:56320
	global_load_lds_dwordx4 v[152:153], off
	s_add_i32 m0, s44, 0x2000
	s_add_u32 s42, s42, 0x40080
	v_lshl_add_u64 v[152:153], v[182:183], 0, s[14:15]
	s_addc_u32 s43, s43, 0
	s_add_i32 s44, s55, s47
	global_load_lds_dwordx4 v[152:153], off
	v_lshl_add_u64 v[152:153], s[42:43], 0, v[132:133]
	s_mov_b32 m0, s44
	s_nop 0
	global_load_lds_dwordx4 v[152:153], off
	v_lshl_add_u64 v[152:153], s[42:43], 0, v[136:137]
	s_add_i32 m0, s44, 0x2000
	s_nop 0
	global_load_lds_dwordx4 v[152:153], off
	v_lshl_add_u64 v[152:153], v[222:223], 0, s[14:15]
	s_mov_b32 m0, s60
	s_nop 0
	global_load_lds_dwordx4 v[152:153], off
	v_lshl_add_u64 v[152:153], v[224:225], 0, s[14:15]
	s_mov_b32 m0, s61
	s_nop 0
	global_load_lds_dwordx4 v[152:153], off
	s_waitcnt vmcnt(8)
	s_waitcnt lgkmcnt(0)
	s_barrier
	s_setprio 1
	s_waitcnt lgkmcnt(0)
	v_mfma_f32_16x16x32_bf16 v[62:65], v[148:151], v[190:193], v[62:65]
	v_mfma_f32_16x16x32_bf16 v[58:61], v[162:165], v[190:193], v[58:61]
	v_mfma_f32_16x16x32_bf16 v[46:49], v[148:151], v[198:201], v[46:49]
	v_mfma_f32_16x16x32_bf16 v[42:45], v[162:165], v[198:201], v[42:45]
	v_mfma_f32_16x16x32_bf16 v[30:33], v[148:151], v[206:209], v[30:33]
	v_mfma_f32_16x16x32_bf16 v[26:29], v[162:165], v[206:209], v[26:29]
	v_mfma_f32_16x16x32_bf16 v[14:17], v[148:151], v[214:217], v[14:17]
	v_mfma_f32_16x16x32_bf16 v[10:13], v[162:165], v[214:217], v[10:13]
	v_mfma_f32_16x16x32_bf16 v[62:65], v[158:161], v[194:197], v[62:65]
	v_mfma_f32_16x16x32_bf16 v[58:61], v[166:169], v[194:197], v[58:61]
	v_mfma_f32_16x16x32_bf16 v[46:49], v[158:161], v[202:205], v[46:49]
	v_mfma_f32_16x16x32_bf16 v[42:45], v[166:169], v[202:205], v[42:45]
	v_mfma_f32_16x16x32_bf16 v[30:33], v[158:161], v[210:213], v[30:33]
	v_mfma_f32_16x16x32_bf16 v[26:29], v[166:169], v[210:213], v[26:29]
	v_mfma_f32_16x16x32_bf16 v[14:17], v[158:161], v[218:221], v[14:17]
	v_mfma_f32_16x16x32_bf16 v[10:13], v[166:169], v[218:221], v[10:13]
	v_mfma_f32_16x16x32_bf16 v[54:57], v[170:173], v[190:193], v[54:57]
	v_mfma_f32_16x16x32_bf16 v[50:53], v[178:181], v[190:193], v[50:53]
	v_mfma_f32_16x16x32_bf16 v[38:41], v[170:173], v[198:201], v[38:41]
	v_mfma_f32_16x16x32_bf16 v[34:37], v[178:181], v[198:201], v[34:37]
	v_mfma_f32_16x16x32_bf16 v[22:25], v[170:173], v[206:209], v[22:25]
	v_mfma_f32_16x16x32_bf16 v[18:21], v[178:181], v[206:209], v[18:21]
	v_mfma_f32_16x16x32_bf16 v[6:9], v[170:173], v[214:217], v[6:9]
	v_mfma_f32_16x16x32_bf16 v[2:5], v[178:181], v[214:217], v[2:5]
	v_mfma_f32_16x16x32_bf16 v[54:57], v[174:177], v[194:197], v[54:57]
	v_mfma_f32_16x16x32_bf16 v[50:53], v[186:189], v[194:197], v[50:53]
	v_mfma_f32_16x16x32_bf16 v[38:41], v[174:177], v[202:205], v[38:41]
	v_mfma_f32_16x16x32_bf16 v[34:37], v[186:189], v[202:205], v[34:37]
	v_mfma_f32_16x16x32_bf16 v[22:25], v[174:177], v[210:213], v[22:25]
	v_mfma_f32_16x16x32_bf16 v[18:21], v[186:189], v[210:213], v[18:21]
	v_mfma_f32_16x16x32_bf16 v[6:9], v[174:177], v[218:221], v[6:9]
	v_mfma_f32_16x16x32_bf16 v[2:5], v[186:189], v[218:221], v[2:5]
	s_setprio 0
	s_barrier
	s_add_i32 s73, s73, 2
	s_add_u32 s40, s40, 0x100
	s_addc_u32 s41, s41, 0
	s_add_u32 s69, s69, 0x100
	s_addc_u32 s72, s72, 0
	s_cmp_gt_u32 s73, 13
	s_cbranch_scc0 .LBB0_814
	s_cmp_gt_i32 s6, 3
	s_cselect_b64 s[40:41], -1, 0
	s_cmp_lt_i32 s6, 4
	s_cbranch_scc1 .LBB0_817
	v_mul_f32_e32 v148, 0xbfb8aa3b, v126
	v_mul_f32_e32 v149, 0xbfb8aa3b, v127
	v_mul_f32_e32 v150, 0xbfb8aa3b, v128
	v_mul_f32_e32 v151, 0xbfb8aa3b, v129
	v_mul_f32_e32 v152, 0xbfb8aa3b, v122
	v_mul_f32_e32 v153, 0xbfb8aa3b, v123
	v_mul_f32_e32 v158, 0xbfb8aa3b, v124
	v_mul_f32_e32 v159, 0xbfb8aa3b, v125
	v_exp_f32_e32 v148, v148
	v_exp_f32_e32 v149, v149
	v_exp_f32_e32 v150, v150
	v_exp_f32_e32 v151, v151
	v_exp_f32_e32 v152, v152
	v_exp_f32_e32 v153, v153
	v_exp_f32_e32 v158, v158
	v_exp_f32_e32 v159, v159
	v_add_f32_e32 v148, 1.0, v148
	v_add_f32_e32 v149, 1.0, v149
	v_add_f32_e32 v150, 1.0, v150
	v_add_f32_e32 v151, 1.0, v151
	v_add_f32_e32 v152, 1.0, v152
	v_add_f32_e32 v153, 1.0, v153
	v_add_f32_e32 v158, 1.0, v158
	v_add_f32_e32 v159, 1.0, v159
	v_rcp_f32_e32 v148, v148
	v_rcp_f32_e32 v149, v149
	v_rcp_f32_e32 v150, v150
	v_rcp_f32_e32 v151, v151
	v_rcp_f32_e32 v152, v152
	v_rcp_f32_e32 v158, v158
	v_rcp_f32_e32 v159, v159
	v_rcp_f32_e32 v153, v153
	v_pk_mul_f32 v[128:129], v[128:129], v[150:151]
	v_pk_mul_f32 v[126:127], v[126:127], v[148:149]
	v_pk_mul_f32 v[124:125], v[124:125], v[158:159]
	v_pk_mul_f32 v[122:123], v[122:123], v[152:153]

.LBB0_1008:
	s_or_b32 s46, s77, 1
	v_add_u32_e32 v140, s66, v143
	s_mul_hi_u32 s55, s46, 0x420000
	s_mul_i32 s54, s46, 0x420000
	s_lshl_b32 s46, s77, 7
	ds_read_b128 v[146:149], v140
	ds_read_b128 v[150:153], v140 offset:1024
	ds_read_b128 v[154:157], v140 offset:2048
	ds_read_b128 v[158:161], v140 offset:3072
	v_add_u32_e32 v140, s67, v143
	s_add_u32 s46, s38, s46
	ds_read_b128 v[162:165], v140
	ds_read_b128 v[166:169], v140 offset:1024
	ds_read_b128 v[170:173], v140 offset:2048
	ds_read_b128 v[174:177], v140 offset:3072
	s_addc_u32 s47, s39, 0
	s_add_u32 s56, s46, 0x100
	s_addc_u32 s57, s47, 0
	s_add_u32 s46, s44, 0x420000
	s_addc_u32 s47, s45, 0
	s_and_b64 s[48:49], exec, s[48:49]
	s_cselect_b32 s49, s25, s57
	s_cselect_b32 s48, s27, s56
	s_add_u32 s54, s75, s54
	s_addc_u32 s55, s76, s55
	v_lshl_add_u64 v[140:141], s[54:55], 0, v[128:129]
	s_add_i32 m0, s37, 0xc000
	ds_read_b128 v[178:181], v145
	ds_read_b128 v[186:189], v145 offset:1024
	ds_read_b128 v[190:193], v145 offset:2048
	ds_read_b128 v[194:197], v145 offset:3072
	ds_read_b128 v[198:201], v145 offset:4096
	ds_read_b128 v[202:205], v145 offset:5120
	ds_read_b128 v[206:209], v145 offset:6144
	ds_read_b128 v[210:213], v145 offset:7168
	global_load_lds_dwordx4 v[140:141], off
	v_lshl_add_u64 v[140:141], s[54:55], 0, v[132:133]
	s_add_i32 m0, s37, 0xe000
	s_nop 0
	global_load_lds_dwordx4 v[140:141], off
	s_waitcnt vmcnt(8)
	s_waitcnt lgkmcnt(0)
	s_barrier
	s_setprio 1
	s_waitcnt lgkmcnt(0)
	v_mfma_f32_16x16x32_bf16 v[124:127], v[146:149], v[178:181], v[124:127]
	v_mfma_f32_16x16x32_bf16 v[120:123], v[154:157], v[178:181], v[120:123]
	v_mfma_f32_16x16x32_bf16 v[116:119], v[146:149], v[190:193], v[116:119]
	v_mfma_f32_16x16x32_bf16 v[108:111], v[154:157], v[190:193], v[108:111]
	v_mfma_f32_16x16x32_bf16 v[100:103], v[146:149], v[198:201], v[100:103]
	v_mfma_f32_16x16x32_bf16 v[92:95], v[154:157], v[198:201], v[92:95]
	v_mfma_f32_16x16x32_bf16 v[84:87], v[146:149], v[206:209], v[84:87]
	v_mfma_f32_16x16x32_bf16 v[76:79], v[154:157], v[206:209], v[76:79]
	v_mfma_f32_16x16x32_bf16 v[124:127], v[150:153], v[186:189], v[124:127]
	v_mfma_f32_16x16x32_bf16 v[120:123], v[158:161], v[186:189], v[120:123]
	v_mfma_f32_16x16x32_bf16 v[116:119], v[150:153], v[194:197], v[116:119]
	v_mfma_f32_16x16x32_bf16 v[108:111], v[158:161], v[194:197], v[108:111]
	v_mfma_f32_16x16x32_bf16 v[100:103], v[150:153], v[202:205], v[100:103]
	v_mfma_f32_16x16x32_bf16 v[92:95], v[158:161], v[202:205], v[92:95]
	v_mfma_f32_16x16x32_bf16 v[84:87], v[150:153], v[210:213], v[84:87]
	v_mfma_f32_16x16x32_bf16 v[76:79], v[158:161], v[210:213], v[76:79]
	v_mfma_f32_16x16x32_bf16 v[112:115], v[162:165], v[178:181], v[112:115]
	v_mfma_f32_16x16x32_bf16 v[104:107], v[170:173], v[178:181], v[104:107]
	v_mfma_f32_16x16x32_bf16 v[96:99], v[162:165], v[190:193], v[96:99]
	v_mfma_f32_16x16x32_bf16 v[88:91], v[170:173], v[190:193], v[88:91]
	v_mfma_f32_16x16x32_bf16 v[80:83], v[162:165], v[198:201], v[80:83]
	v_mfma_f32_16x16x32_bf16 v[72:75], v[170:173], v[198:201], v[72:75]
	v_mfma_f32_16x16x32_bf16 v[68:71], v[162:165], v[206:209], v[68:71]
	v_mfma_f32_16x16x32_bf16 v[64:67], v[170:173], v[206:209], v[64:67]
	v_mfma_f32_16x16x32_bf16 v[112:115], v[166:169], v[186:189], v[112:115]
	v_mfma_f32_16x16x32_bf16 v[104:107], v[174:177], v[186:189], v[104:107]
	v_mfma_f32_16x16x32_bf16 v[96:99], v[166:169], v[194:197], v[96:99]
	v_mfma_f32_16x16x32_bf16 v[88:91], v[174:177], v[194:197], v[88:91]
	v_mfma_f32_16x16x32_bf16 v[80:83], v[166:169], v[202:205], v[80:83]
	v_mfma_f32_16x16x32_bf16 v[72:75], v[174:177], v[202:205], v[72:75]
	v_mfma_f32_16x16x32_bf16 v[68:71], v[166:169], v[210:213], v[68:71]
	v_mfma_f32_16x16x32_bf16 v[64:67], v[174:177], v[210:213], v[64:67]
	s_setprio 0
	s_barrier
	s_add_i32 s54, s66, s50
	v_lshl_add_u64 v[140:141], s[48:49], 0, v[130:131]
	s_mov_b32 m0, s54
	ds_read_b128 v[178:181], v145 offset:16384
	ds_read_b128 v[186:189], v145 offset:17408
	ds_read_b128 v[190:193], v145 offset:18432
	ds_read_b128 v[194:197], v145 offset:19456
	ds_read_b128 v[198:201], v145 offset:20480
	ds_read_b128 v[202:205], v145 offset:21504
	ds_read_b128 v[206:209], v145 offset:22528
	ds_read_b128 v[210:213], v145 offset:23552
	global_load_lds_dwordx4 v[140:141], off
	s_add_i32 m0, s54, 0x2000
	s_add_u32 s54, s48, 0x40000
	v_lshl_add_u64 v[182:183], s[48:49], 0, v[134:135]
	s_addc_u32 s55, s49, 0
	s_add_i32 s56, s67, s50
	global_load_lds_dwordx4 v[182:183], off
	v_lshl_add_u64 v[214:215], s[54:55], 0, v[130:131]
	s_mov_b32 m0, s56
	s_nop 0
	global_load_lds_dwordx4 v[214:215], off
	v_lshl_add_u64 v[214:215], s[54:55], 0, v[134:135]
	s_add_i32 m0, s56, 0x2000
	s_nop 0
	global_load_lds_dwordx4 v[214:215], off
	v_lshl_add_u64 v[214:215], s[44:45], 0, v[128:129]
	s_mov_b32 m0, s37
	s_nop 0
	global_load_lds_dwordx4 v[214:215], off
	v_lshl_add_u64 v[214:215], s[44:45], 0, v[132:133]
	s_mov_b32 m0, s58
	s_nop 0
	global_load_lds_dwordx4 v[214:215], off
	s_waitcnt vmcnt(8)
	s_waitcnt lgkmcnt(0)
	s_barrier
	s_setprio 1
	s_waitcnt lgkmcnt(0)
	v_mfma_f32_16x16x32_bf16 v[60:63], v[146:149], v[178:181], v[60:63]
	v_mfma_f32_16x16x32_bf16 v[56:59], v[154:157], v[178:181], v[56:59]
	v_mfma_f32_16x16x32_bf16 v[52:55], v[146:149], v[190:193], v[52:55]
	v_mfma_f32_16x16x32_bf16 v[44:47], v[154:157], v[190:193], v[44:47]
	v_mfma_f32_16x16x32_bf16 v[36:39], v[146:149], v[198:201], v[36:39]
	v_mfma_f32_16x16x32_bf16 v[28:31], v[154:157], v[198:201], v[28:31]
	v_mfma_f32_16x16x32_bf16 v[20:23], v[146:149], v[206:209], v[20:23]
	v_mfma_f32_16x16x32_bf16 v[12:15], v[154:157], v[206:209], v[12:15]
	v_mfma_f32_16x16x32_bf16 v[60:63], v[150:153], v[186:189], v[60:63]
	v_mfma_f32_16x16x32_bf16 v[56:59], v[158:161], v[186:189], v[56:59]
	v_mfma_f32_16x16x32_bf16 v[52:55], v[150:153], v[194:197], v[52:55]
	v_mfma_f32_16x16x32_bf16 v[44:47], v[158:161], v[194:197], v[44:47]
	v_mfma_f32_16x16x32_bf16 v[36:39], v[150:153], v[202:205], v[36:39]
	v_mfma_f32_16x16x32_bf16 v[28:31], v[158:161], v[202:205], v[28:31]
	v_mfma_f32_16x16x32_bf16 v[20:23], v[150:153], v[210:213], v[20:23]
	v_mfma_f32_16x16x32_bf16 v[12:15], v[158:161], v[210:213], v[12:15]
	v_mfma_f32_16x16x32_bf16 v[48:51], v[162:165], v[178:181], v[48:51]
	v_mfma_f32_16x16x32_bf16 v[40:43], v[170:173], v[178:181], v[40:43]
	v_mfma_f32_16x16x32_bf16 v[32:35], v[162:165], v[190:193], v[32:35]
	v_mfma_f32_16x16x32_bf16 v[24:27], v[170:173], v[190:193], v[24:27]
	v_mfma_f32_16x16x32_bf16 v[16:19], v[162:165], v[198:201], v[16:19]
	v_mfma_f32_16x16x32_bf16 v[8:11], v[170:173], v[198:201], v[8:11]
	v_mfma_f32_16x16x32_bf16 v[4:7], v[162:165], v[206:209], v[4:7]
	v_mfma_f32_16x16x32_bf16 v[0:3], v[170:173], v[206:209], v[0:3]
	v_mfma_f32_16x16x32_bf16 v[48:51], v[166:169], v[186:189], v[48:51]
	v_mfma_f32_16x16x32_bf16 v[40:43], v[174:177], v[186:189], v[40:43]
	v_mfma_f32_16x16x32_bf16 v[32:35], v[166:169], v[194:197], v[32:35]
	v_mfma_f32_16x16x32_bf16 v[24:27], v[174:177], v[194:197], v[24:27]
	v_mfma_f32_16x16x32_bf16 v[16:19], v[166:169], v[202:205], v[16:19]
	v_mfma_f32_16x16x32_bf16 v[8:11], v[174:177], v[202:205], v[8:11]
	v_mfma_f32_16x16x32_bf16 v[4:7], v[166:169], v[210:213], v[4:7]
	v_mfma_f32_16x16x32_bf16 v[0:3], v[174:177], v[210:213], v[0:3]
	s_setprio 0
	s_barrier
	s_add_i32 s54, 0, 0x18000
	s_add_i32 s55, 0, 0x1c000
	v_add_u32_e32 v158, s54, v143
	v_add_u32_e32 v174, s55, v143
	ds_read_b128 v[146:149], v158
	ds_read_b128 v[150:153], v158 offset:1024
	ds_read_b128 v[154:157], v158 offset:2048
	ds_read_b128 v[158:161], v158 offset:3072
	ds_read_b128 v[162:165], v174
	ds_read_b128 v[166:169], v174 offset:1024
	ds_read_b128 v[170:173], v174 offset:2048
	ds_read_b128 v[174:177], v174 offset:3072
	s_add_u32 s44, s44, 0x4000
	s_addc_u32 s45, s45, 0
	s_mov_b32 m0, s59
	v_lshl_add_u64 v[214:215], s[44:45], 0, v[128:129]
	ds_read_b128 v[178:181], v145 offset:32768
	ds_read_b128 v[186:189], v145 offset:33792
	ds_read_b128 v[190:193], v145 offset:34816
	ds_read_b128 v[194:197], v145 offset:35840
	ds_read_b128 v[198:201], v145 offset:36864
	ds_read_b128 v[202:205], v145 offset:37888
	ds_read_b128 v[206:209], v145 offset:38912
	ds_read_b128 v[210:213], v145 offset:39936
	global_load_lds_dwordx4 v[214:215], off
	v_lshl_add_u64 v[214:215], s[44:45], 0, v[132:133]
	s_mov_b32 m0, s60
	s_nop 0
	global_load_lds_dwordx4 v[214:215], off
	s_waitcnt vmcnt(8)
	s_waitcnt lgkmcnt(0)
	s_barrier
	s_setprio 1
	s_waitcnt lgkmcnt(0)
	v_mfma_f32_16x16x32_bf16 v[124:127], v[146:149], v[178:181], v[124:127]
	v_mfma_f32_16x16x32_bf16 v[120:123], v[154:157], v[178:181], v[120:123]
	v_mfma_f32_16x16x32_bf16 v[116:119], v[146:149], v[190:193], v[116:119]
	v_mfma_f32_16x16x32_bf16 v[108:111], v[154:157], v[190:193], v[108:111]
	v_mfma_f32_16x16x32_bf16 v[100:103], v[146:149], v[198:201], v[100:103]
	v_mfma_f32_16x16x32_bf16 v[92:95], v[154:157], v[198:201], v[92:95]
	v_mfma_f32_16x16x32_bf16 v[84:87], v[146:149], v[206:209], v[84:87]
	v_mfma_f32_16x16x32_bf16 v[76:79], v[154:157], v[206:209], v[76:79]
	v_mfma_f32_16x16x32_bf16 v[124:127], v[150:153], v[186:189], v[124:127]
	v_mfma_f32_16x16x32_bf16 v[120:123], v[158:161], v[186:189], v[120:123]
	v_mfma_f32_16x16x32_bf16 v[116:119], v[150:153], v[194:197], v[116:119]
	v_mfma_f32_16x16x32_bf16 v[108:111], v[158:161], v[194:197], v[108:111]
	v_mfma_f32_16x16x32_bf16 v[100:103], v[150:153], v[202:205], v[100:103]
	v_mfma_f32_16x16x32_bf16 v[92:95], v[158:161], v[202:205], v[92:95]
	v_mfma_f32_16x16x32_bf16 v[84:87], v[150:153], v[210:213], v[84:87]
	v_mfma_f32_16x16x32_bf16 v[76:79], v[158:161], v[210:213], v[76:79]
	v_mfma_f32_16x16x32_bf16 v[112:115], v[162:165], v[178:181], v[112:115]
	v_mfma_f32_16x16x32_bf16 v[104:107], v[170:173], v[178:181], v[104:107]
	v_mfma_f32_16x16x32_bf16 v[96:99], v[162:165], v[190:193], v[96:99]
	v_mfma_f32_16x16x32_bf16 v[88:91], v[170:173], v[190:193], v[88:91]
	v_mfma_f32_16x16x32_bf16 v[80:83], v[162:165], v[198:201], v[80:83]
	v_mfma_f32_16x16x32_bf16 v[72:75], v[170:173], v[198:201], v[72:75]
	v_mfma_f32_16x16x32_bf16 v[68:71], v[162:165], v[206:209], v[68:71]
	v_mfma_f32_16x16x32_bf16 v[64:67], v[170:173], v[206:209], v[64:67]
	v_mfma_f32_16x16x32_bf16 v[112:115], v[166:169], v[186:189], v[112:115]
	v_mfma_f32_16x16x32_bf16 v[104:107], v[174:177], v[186:189], v[104:107]
	v_mfma_f32_16x16x32_bf16 v[96:99], v[166:169], v[194:197], v[96:99]
	v_mfma_f32_16x16x32_bf16 v[88:91], v[174:177], v[194:197], v[88:91]
	v_mfma_f32_16x16x32_bf16 v[80:83], v[166:169], v[202:205], v[80:83]
	v_mfma_f32_16x16x32_bf16 v[72:75], v[174:177], v[202:205], v[72:75]
	v_mfma_f32_16x16x32_bf16 v[68:71], v[166:169], v[210:213], v[68:71]
	v_mfma_f32_16x16x32_bf16 v[64:67], v[174:177], v[210:213], v[64:67]
	s_setprio 0
	s_barrier
	s_add_i32 s44, s54, s50
	v_lshl_add_u64 v[140:141], v[140:141], 0, s[14:15]
	s_mov_b32 m0, s44
	ds_read_b128 v[178:181], v145 offset:49152
	ds_read_b128 v[186:189], v145 offset:50176
	ds_read_b128 v[190:193], v145 offset:51200
	ds_read_b128 v[194:197], v145 offset:52224
	ds_read_b128 v[198:201], v145 offset:53248
	ds_read_b128 v[202:205], v145 offset:54272
	ds_read_b128 v[206:209], v145 offset:55296
	ds_read_b128 v[210:213], v145 offset:56320
	global_load_lds_dwordx4 v[140:141], off
	s_add_i32 m0, s44, 0x2000
	s_add_u32 s44, s48, 0x40080
	v_lshl_add_u64 v[140:141], v[182:183], 0, s[14:15]
	s_addc_u32 s45, s49, 0
	s_add_i32 s48, s55, s50
	global_load_lds_dwordx4 v[140:141], off
	v_lshl_add_u64 v[140:141], s[44:45], 0, v[130:131]
	s_mov_b32 m0, s48
	s_nop 0
	global_load_lds_dwordx4 v[140:141], off
	v_lshl_add_u64 v[140:141], s[44:45], 0, v[134:135]
	s_add_i32 m0, s48, 0x2000
	s_nop 0
	global_load_lds_dwordx4 v[140:141], off
	v_lshl_add_u64 v[140:141], s[46:47], 0, v[128:129]
	s_mov_b32 m0, s63
	s_nop 0
	global_load_lds_dwordx4 v[140:141], off
	v_lshl_add_u64 v[140:141], s[46:47], 0, v[132:133]
	s_mov_b32 m0, s64
	s_nop 0
	global_load_lds_dwordx4 v[140:141], off
	s_waitcnt vmcnt(8)
	s_waitcnt lgkmcnt(0)
	s_barrier
	s_setprio 1
	s_waitcnt lgkmcnt(0)
	v_mfma_f32_16x16x32_bf16 v[60:63], v[146:149], v[178:181], v[60:63]
	v_mfma_f32_16x16x32_bf16 v[56:59], v[154:157], v[178:181], v[56:59]
	v_mfma_f32_16x16x32_bf16 v[52:55], v[146:149], v[190:193], v[52:55]
	v_mfma_f32_16x16x32_bf16 v[44:47], v[154:157], v[190:193], v[44:47]
	v_mfma_f32_16x16x32_bf16 v[36:39], v[146:149], v[198:201], v[36:39]
	v_mfma_f32_16x16x32_bf16 v[28:31], v[154:157], v[198:201], v[28:31]
	v_mfma_f32_16x16x32_bf16 v[20:23], v[146:149], v[206:209], v[20:23]
	v_mfma_f32_16x16x32_bf16 v[12:15], v[154:157], v[206:209], v[12:15]
	v_mfma_f32_16x16x32_bf16 v[60:63], v[150:153], v[186:189], v[60:63]
	v_mfma_f32_16x16x32_bf16 v[56:59], v[158:161], v[186:189], v[56:59]
	v_mfma_f32_16x16x32_bf16 v[52:55], v[150:153], v[194:197], v[52:55]
	v_mfma_f32_16x16x32_bf16 v[44:47], v[158:161], v[194:197], v[44:47]
	v_mfma_f32_16x16x32_bf16 v[36:39], v[150:153], v[202:205], v[36:39]
	v_mfma_f32_16x16x32_bf16 v[28:31], v[158:161], v[202:205], v[28:31]
	v_mfma_f32_16x16x32_bf16 v[20:23], v[150:153], v[210:213], v[20:23]
	v_mfma_f32_16x16x32_bf16 v[12:15], v[158:161], v[210:213], v[12:15]
	v_mfma_f32_16x16x32_bf16 v[48:51], v[162:165], v[178:181], v[48:51]
	v_mfma_f32_16x16x32_bf16 v[40:43], v[170:173], v[178:181], v[40:43]
	v_mfma_f32_16x16x32_bf16 v[32:35], v[162:165], v[190:193], v[32:35]
	v_mfma_f32_16x16x32_bf16 v[24:27], v[170:173], v[190:193], v[24:27]
	v_mfma_f32_16x16x32_bf16 v[16:19], v[162:165], v[198:201], v[16:19]
	v_mfma_f32_16x16x32_bf16 v[8:11], v[170:173], v[198:201], v[8:11]
	v_mfma_f32_16x16x32_bf16 v[4:7], v[162:165], v[206:209], v[4:7]
	v_mfma_f32_16x16x32_bf16 v[0:3], v[170:173], v[206:209], v[0:3]
	v_mfma_f32_16x16x32_bf16 v[48:51], v[166:169], v[186:189], v[48:51]
	v_mfma_f32_16x16x32_bf16 v[40:43], v[174:177], v[186:189], v[40:43]
	v_mfma_f32_16x16x32_bf16 v[32:35], v[166:169], v[194:197], v[32:35]
	v_mfma_f32_16x16x32_bf16 v[24:27], v[174:177], v[194:197], v[24:27]
	v_mfma_f32_16x16x32_bf16 v[16:19], v[166:169], v[202:205], v[16:19]
	v_mfma_f32_16x16x32_bf16 v[8:11], v[174:177], v[202:205], v[8:11]
	v_mfma_f32_16x16x32_bf16 v[4:7], v[166:169], v[210:213], v[4:7]
	v_mfma_f32_16x16x32_bf16 v[0:3], v[174:177], v[210:213], v[0:3]
	s_setprio 0
	s_barrier
	s_cmp_gt_u32 s77, 13
	s_mov_b32 s77, s78
	s_cbranch_scc1 .LBB0_1000
